# phase 0 bf16 weight stores marked nt (streaming), on the rowss-wait + static-priority version
# baseline (speedup 1.0000x reference)
; #define GAS __attribute__((address_space(1)))
; #define LAS __attribute__((address_space(3)))
; __device__ __forceinline__ unsigned pk2(float lo, float hi) { const f32x2_t_ v = {lo, hi}; return __builtin_bit_cast(unsigned, __builtin_convertvector(v, bf16x2_t_)); }
; __device__ __forceinline__ void p0_transpose_item(const float* W, int K, int N, bf16* WT, const float* gain, LAS float* scr, int item, int lane) {
;     ...
;     for (int j = 0; j < 4; ++j) { const int n = (lane >> 3) + 8 * j; const LAS float* s = scr + (8 * c) * 36 + n;
;         v4u o; o.x = pk2(s[0 * 36], s[1 * 36]); o.y = pk2(s[2 * 36], s[3 * 36]); o.z = pk2(s[4 * 36], s[5 * 36]); o.w = pk2(s[6 * 36], s[7 * 36]);
;         *(GAS v4u*)(WT + (size_t)(n0 + n) * K + k0 + 8 * c) = o; }
.Lp0_ng_21:
	v_cvt_pk_bf16_f32 v110, v10, v14
	v_cvt_pk_bf16_f32 v111, v18, v22
	v_cvt_pk_bf16_f32 v112, v26, v30
	v_cvt_pk_bf16_f32 v113, v34, v38
	global_store_dwordx4 v50, v[110:113], s[10:11] nt
	s_add_u32 s10, s10, s12
	s_addc_u32 s11, s11, 0
	v_cvt_pk_bf16_f32 v114, v11, v15
	v_cvt_pk_bf16_f32 v115, v19, v23
	v_cvt_pk_bf16_f32 v116, v27, v31
	v_cvt_pk_bf16_f32 v117, v35, v39
	global_store_dwordx4 v50, v[114:117], s[10:11] nt
	s_add_u32 s10, s10, s12
	s_addc_u32 s11, s11, 0
	v_cvt_pk_bf16_f32 v118, v12, v16
	v_cvt_pk_bf16_f32 v119, v20, v24
	v_cvt_pk_bf16_f32 v120, v28, v32
	v_cvt_pk_bf16_f32 v121, v36, v40
	global_store_dwordx4 v50, v[118:121], s[10:11] nt
	s_add_u32 s10, s10, s12
	s_addc_u32 s11, s11, 0
	v_cvt_pk_bf16_f32 v122, v13, v17
	v_cvt_pk_bf16_f32 v123, v21, v25
	v_cvt_pk_bf16_f32 v124, v29, v33
	v_cvt_pk_bf16_f32 v125, v37, v41
	global_store_dwordx4 v50, v[122:125], s[10:11] nt

; #define GAS __attribute__((address_space(1)))
; #define LAS __attribute__((address_space(3)))
; __device__ __forceinline__ unsigned pk2(float lo, float hi) { const f32x2_t_ v = {lo, hi}; return __builtin_bit_cast(unsigned, __builtin_convertvector(v, bf16x2_t_)); }
; __device__ __forceinline__ void p0_transpose_item(const float* W, int K, int N, bf16* WT, const float* gain, LAS float* scr, int item, int lane) {
;     ...
;     for (int j = 0; j < 4; ++j) { const int n = (lane >> 3) + 8 * j; const LAS float* s = scr + (8 * c) * 36 + n;
;         v4u o; o.x = pk2(s[0 * 36], s[1 * 36]); o.y = pk2(s[2 * 36], s[3 * 36]); o.z = pk2(s[4 * 36], s[5 * 36]); o.w = pk2(s[6 * 36], s[7 * 36]);
;         *(GAS v4u*)(WT + (size_t)(n0 + n) * K + k0 + 8 * c) = o; }
; __device__ __forceinline__ void p0_prologue(Frame& F, const float* x, bf16* hb, unsigned long long* rowss0) {
;     ...
;     for (int it = gw; it < NITEMS; it += NGW) {
;         int r = it;
;         if (r < I_SIN) { p0_transpose_item(ldin(2), D, SSD_IN, (bf16*)(ws + WS_W_SSD0_IN), ldin(1), scr, r, F.lane); continue; } r -= I_SIN;
;         if (r < I_SOUT) { p0_transpose_item(ldin(9), SSD_DI, D, (bf16*)(ws + WS_W_SSD0_OUT), ldin(8), scr, r, F.lane); continue; } r -= I_SOUT;
;         if (r < I_PIN) { p0_transpose_item(ldin(11), D, 16384, (bf16*)(ws + WS_W_POOL_IN), ldin(10), scr, r, F.lane); continue; } r -= I_PIN;
;         if (r < 4 * I_PG) { const int g = r / I_PG; p0_transpose_item(ldin(12) + (size_t)g * 2048 * 2048, 2048, 2048, (bf16*)(ws + WS_W_POOL_GRP) + (size_t)g * 2048 * 2048, nullptr, scr, r % I_PG, F.lane); continue; } r -= 4 * I_PG;
;         if (r < I_POUT) { p0_transpose_item(ldin(15), POOL_W, D, (bf16*)(ws + WS_W_POOL_OUT), nullptr, scr, r, F.lane); continue; } r -= I_POUT;
;         if (r < I_MIN) { p0_transpose_item(ldin(17), D, 16384, (bf16*)(ws + WS_W_MOBA_IN), ldin(16), scr, r, F.lane); continue; } r -= I_MIN;
;         if (r < I_MOUT) { p0_transpose_item(ldin(20), D, D, (bf16*)(ws + WS_W_MOBA_OUT), nullptr, scr, r, F.lane); continue; } r -= I_MOUT;
;         if (r < I_SIN) { p0_transpose_item(ldin(22), D, SSD_IN, (bf16*)(ws + WS_W_SSD3_IN), ldin(21), scr, r, F.lane); continue; } r -= I_SIN;
;         p0_transpose_item(ldin(29), SSD_DI, D, (bf16*)(ws + WS_W_SSD3_OUT), ldin(28), scr, r, F.lane);
.Lp0_ng_32:
	v_cvt_pk_bf16_f32 v130, v60, v64
	v_cvt_pk_bf16_f32 v131, v68, v72
	v_cvt_pk_bf16_f32 v132, v76, v80
	v_cvt_pk_bf16_f32 v133, v84, v88
	global_store_dwordx4 v100, v[130:133], s[14:15] nt
	s_add_u32 s14, s14, s16
	s_addc_u32 s15, s15, 0
	v_cvt_pk_bf16_f32 v134, v61, v65
	v_cvt_pk_bf16_f32 v135, v69, v73
	v_cvt_pk_bf16_f32 v136, v77, v81
	v_cvt_pk_bf16_f32 v137, v85, v89
	global_store_dwordx4 v100, v[134:137], s[14:15] nt
	s_add_u32 s14, s14, s16
	s_addc_u32 s15, s15, 0
	v_cvt_pk_bf16_f32 v138, v62, v66
	v_cvt_pk_bf16_f32 v139, v70, v74
	v_cvt_pk_bf16_f32 v140, v78, v82
	v_cvt_pk_bf16_f32 v141, v86, v90
	global_store_dwordx4 v100, v[138:141], s[14:15] nt
	s_add_u32 s14, s14, s16
	s_addc_u32 s15, s15, 0
	v_cvt_pk_bf16_f32 v142, v63, v67
	v_cvt_pk_bf16_f32 v143, v71, v75
	v_cvt_pk_bf16_f32 v144, v79, v83
	v_cvt_pk_bf16_f32 v145, v87, v91
	global_store_dwordx4 v100, v[142:145], s[14:15] nt
	s_cmp_ge_u32 s64, 205312
	s_cbranch_scc1 .Lp0_tailA
	s_cmp_lt_u32 s64, 37120
	s_cbranch_scc1 .Lp0_m0_34
	s_cmp_lt_u32 s64, 53504
	s_cbranch_scc1 .Lp0_m1_35
	s_cmp_lt_u32 s64, 86272
	s_cbranch_scc1 .Lp0_m2_36
	s_cmp_lt_u32 s64, 94464
	s_cbranch_scc1 .Lp0_m3_37
	s_cmp_lt_u32 s64, 110848
	s_cbranch_scc1 .Lp0_m4_38
	s_cmp_lt_u32 s64, 143616
	s_cbranch_scc1 .Lp0_m5_39
	s_cmp_lt_u32 s64, 151808
	s_cbranch_scc1 .Lp0_m6_40
	s_cmp_lt_u32 s64, 188928
	s_cbranch_scc1 .Lp0_m7_41
	s_branch .Lp0_m8_42

; #define GAS __attribute__((address_space(1)))
; #define LAS __attribute__((address_space(3)))
; __device__ __forceinline__ unsigned pk2(float lo, float hi) { const f32x2_t_ v = {lo, hi}; return __builtin_bit_cast(unsigned, __builtin_convertvector(v, bf16x2_t_)); }
; __device__ __forceinline__ void p0_transpose_item(const float* W, int K, int N, bf16* WT, const float* gain, LAS float* scr, int item, int lane) {
;     ...
;     for (int j = 0; j < 4; ++j) { const int n = (lane >> 3) + 8 * j; const LAS float* s = scr + (8 * c) * 36 + n;
;         v4u o; o.x = pk2(s[0 * 36], s[1 * 36]); o.y = pk2(s[2 * 36], s[3 * 36]); o.z = pk2(s[4 * 36], s[5 * 36]); o.w = pk2(s[6 * 36], s[7 * 36]);
;         *(GAS v4u*)(WT + (size_t)(n0 + n) * K + k0 + 8 * c) = o; }
.Lp0_ng_43:
	v_cvt_pk_bf16_f32 v110, v10, v14
	v_cvt_pk_bf16_f32 v111, v18, v22
	v_cvt_pk_bf16_f32 v112, v26, v30
	v_cvt_pk_bf16_f32 v113, v34, v38
	global_store_dwordx4 v50, v[110:113], s[10:11] nt
	s_add_u32 s10, s10, s12
	s_addc_u32 s11, s11, 0
	v_cvt_pk_bf16_f32 v114, v11, v15
	v_cvt_pk_bf16_f32 v115, v19, v23
	v_cvt_pk_bf16_f32 v116, v27, v31
	v_cvt_pk_bf16_f32 v117, v35, v39
	global_store_dwordx4 v50, v[114:117], s[10:11] nt
	s_add_u32 s10, s10, s12
	s_addc_u32 s11, s11, 0
	v_cvt_pk_bf16_f32 v118, v12, v16
	v_cvt_pk_bf16_f32 v119, v20, v24
	v_cvt_pk_bf16_f32 v120, v28, v32
	v_cvt_pk_bf16_f32 v121, v36, v40
	global_store_dwordx4 v50, v[118:121], s[10:11] nt
	s_add_u32 s10, s10, s12
	s_addc_u32 s11, s11, 0
	v_cvt_pk_bf16_f32 v122, v13, v17
	v_cvt_pk_bf16_f32 v123, v21, v25
	v_cvt_pk_bf16_f32 v124, v29, v33
	v_cvt_pk_bf16_f32 v125, v37, v41
	global_store_dwordx4 v50, v[122:125], s[10:11] nt
	s_branch .Lp0_loop

; #define GAS __attribute__((address_space(1)))
; #define LAS __attribute__((address_space(3)))
; __device__ __forceinline__ unsigned pk2(float lo, float hi) { const f32x2_t_ v = {lo, hi}; return __builtin_bit_cast(unsigned, __builtin_convertvector(v, bf16x2_t_)); }
; __device__ __forceinline__ void p0_transpose_item(const float* W, int K, int N, bf16* WT, const float* gain, LAS float* scr, int item, int lane) {
;     ...
;     for (int j = 0; j < 4; ++j) { const int n = (lane >> 3) + 8 * j; const LAS float* s = scr + (8 * c) * 36 + n;
;         v4u o; o.x = pk2(s[0 * 36], s[1 * 36]); o.y = pk2(s[2 * 36], s[3 * 36]); o.z = pk2(s[4 * 36], s[5 * 36]); o.w = pk2(s[6 * 36], s[7 * 36]);
;         *(GAS v4u*)(WT + (size_t)(n0 + n) * K + k0 + 8 * c) = o; }
.Lp0_ng_44:
	v_cvt_pk_bf16_f32 v130, v60, v64
	v_cvt_pk_bf16_f32 v131, v68, v72
	v_cvt_pk_bf16_f32 v132, v76, v80
	v_cvt_pk_bf16_f32 v133, v84, v88
	global_store_dwordx4 v100, v[130:133], s[14:15] nt
	s_add_u32 s14, s14, s16
	s_addc_u32 s15, s15, 0
	v_cvt_pk_bf16_f32 v134, v61, v65
	v_cvt_pk_bf16_f32 v135, v69, v73
	v_cvt_pk_bf16_f32 v136, v77, v81
	v_cvt_pk_bf16_f32 v137, v85, v89
	global_store_dwordx4 v100, v[134:137], s[14:15] nt
	s_add_u32 s14, s14, s16
	s_addc_u32 s15, s15, 0
	v_cvt_pk_bf16_f32 v138, v62, v66
	v_cvt_pk_bf16_f32 v139, v70, v74
	v_cvt_pk_bf16_f32 v140, v78, v82
	v_cvt_pk_bf16_f32 v141, v86, v90
	global_store_dwordx4 v100, v[138:141], s[14:15] nt
	s_add_u32 s14, s14, s16
	s_addc_u32 s15, s15, 0
	v_cvt_pk_bf16_f32 v142, v63, v67
	v_cvt_pk_bf16_f32 v143, v71, v75
	v_cvt_pk_bf16_f32 v144, v79, v83
	v_cvt_pk_bf16_f32 v145, v87, v91
	global_store_dwordx4 v100, v[142:145], s[14:15] nt
	s_branch .Lp0_x
